# MoBA key-mean reduction restructured: 32 independent loads per step (8 steps), same summation order
# baseline (speedup 1.0000x reference)
.LBB0_1297:
	s_lshl_b32 s36, s5, 12
	v_lshl_add_u64 v[12:13], v[10:11], 0, s[36:37]
	global_load_ushort v116, v[12:13], off
	global_load_ushort v117, v[12:13], off offset:16
	global_load_ushort v118, v[12:13], off offset:32
	global_load_ushort v119, v[12:13], off offset:48
	global_load_ushort v120, v[12:13], off offset:64
	global_load_ushort v121, v[12:13], off offset:80
	global_load_ushort v122, v[12:13], off offset:96
	global_load_ushort v123, v[12:13], off offset:112
	global_load_ushort v124, v[12:13], off offset:128
	global_load_ushort v125, v[12:13], off offset:144
	global_load_ushort v126, v[12:13], off offset:160
	global_load_ushort v127, v[12:13], off offset:176
	global_load_ushort v128, v[12:13], off offset:192
	global_load_ushort v129, v[12:13], off offset:208
	global_load_ushort v130, v[12:13], off offset:224
	global_load_ushort v131, v[12:13], off offset:240
	global_load_ushort v132, v[12:13], off offset:256
	global_load_ushort v133, v[12:13], off offset:272
	global_load_ushort v134, v[12:13], off offset:288
	global_load_ushort v135, v[12:13], off offset:304
	global_load_ushort v136, v[12:13], off offset:320
	global_load_ushort v137, v[12:13], off offset:336
	global_load_ushort v138, v[12:13], off offset:352
	global_load_ushort v139, v[12:13], off offset:368
	global_load_ushort v140, v[12:13], off offset:384
	global_load_ushort v141, v[12:13], off offset:400
	global_load_ushort v142, v[12:13], off offset:416
	global_load_ushort v143, v[12:13], off offset:432
	global_load_ushort v144, v[12:13], off offset:448
	global_load_ushort v145, v[12:13], off offset:464
	global_load_ushort v146, v[12:13], off offset:480
	global_load_ushort v147, v[12:13], off offset:496
	s_add_i32 s5, s5, 1
	s_cmp_eq_u32 s5, 8
	s_waitcnt vmcnt(0)
	v_lshlrev_b32_e32 v116, 16, v116
	v_add_f32_e32 v0, v0, v116
	v_lshlrev_b32_e32 v117, 16, v117
	v_add_f32_e32 v0, v0, v117
	v_lshlrev_b32_e32 v118, 16, v118
	v_add_f32_e32 v0, v0, v118
	v_lshlrev_b32_e32 v119, 16, v119
	v_add_f32_e32 v0, v0, v119
	v_lshlrev_b32_e32 v120, 16, v120
	v_add_f32_e32 v0, v0, v120
	v_lshlrev_b32_e32 v121, 16, v121
	v_add_f32_e32 v0, v0, v121
	v_lshlrev_b32_e32 v122, 16, v122
	v_add_f32_e32 v0, v0, v122
	v_lshlrev_b32_e32 v123, 16, v123
	v_add_f32_e32 v0, v0, v123
	v_lshlrev_b32_e32 v124, 16, v124
	v_add_f32_e32 v0, v0, v124
	v_lshlrev_b32_e32 v125, 16, v125
	v_add_f32_e32 v0, v0, v125
	v_lshlrev_b32_e32 v126, 16, v126
	v_add_f32_e32 v0, v0, v126
	v_lshlrev_b32_e32 v127, 16, v127
	v_add_f32_e32 v0, v0, v127
	v_lshlrev_b32_e32 v128, 16, v128
	v_add_f32_e32 v0, v0, v128
	v_lshlrev_b32_e32 v129, 16, v129
	v_add_f32_e32 v0, v0, v129
	v_lshlrev_b32_e32 v130, 16, v130
	v_add_f32_e32 v0, v0, v130
	v_lshlrev_b32_e32 v131, 16, v131
	v_add_f32_e32 v0, v0, v131
	v_lshlrev_b32_e32 v132, 16, v132
	v_add_f32_e32 v0, v0, v132
	v_lshlrev_b32_e32 v133, 16, v133
	v_add_f32_e32 v0, v0, v133
	v_lshlrev_b32_e32 v134, 16, v134
	v_add_f32_e32 v0, v0, v134
	v_lshlrev_b32_e32 v135, 16, v135
	v_add_f32_e32 v0, v0, v135
	v_lshlrev_b32_e32 v136, 16, v136
	v_add_f32_e32 v0, v0, v136
	v_lshlrev_b32_e32 v137, 16, v137
	v_add_f32_e32 v0, v0, v137
	v_lshlrev_b32_e32 v138, 16, v138
	v_add_f32_e32 v0, v0, v138
	v_lshlrev_b32_e32 v139, 16, v139
	v_add_f32_e32 v0, v0, v139
	v_lshlrev_b32_e32 v140, 16, v140
	v_add_f32_e32 v0, v0, v140
	v_lshlrev_b32_e32 v141, 16, v141
	v_add_f32_e32 v0, v0, v141
	v_lshlrev_b32_e32 v142, 16, v142
	v_add_f32_e32 v0, v0, v142
	v_lshlrev_b32_e32 v143, 16, v143
	v_add_f32_e32 v0, v0, v143
	v_lshlrev_b32_e32 v144, 16, v144
	v_add_f32_e32 v0, v0, v144
	v_lshlrev_b32_e32 v145, 16, v145
	v_add_f32_e32 v0, v0, v145
	v_lshlrev_b32_e32 v146, 16, v146
	v_add_f32_e32 v0, v0, v146
	v_lshlrev_b32_e32 v147, 16, v147
	v_add_f32_e32 v0, v0, v147
	s_cbranch_scc0 .LBB0_1297
	s_lshl_b64 s[2:3], s[2:3], 8
	v_mul_f32_e32 v0, 0x3b800000, v0
	v_lshl_add_u64 v[10:11], v[4:5], 0, s[2:3]
	global_store_dword v[10:11], v0, off
	s_branch .LBB0_1294
